# down-GEMM epilogue: first-half residual x loads hoisted above the gate-vector loads (3 serialized round trips -> 1)
# speedup vs baseline: 1.0037x; 1.0004x over previous
;     __device__ __forceinline__ void operator()(const f32x4 (&acc)[2][2][4][2], const Unit& u, int wr, int wc, int fr, int fq) const {
;         const int c00 = u.pn * 256 + wc * 32 + 8 * fq;
; #pragma unroll
;         for (int ai = 0; ai < 2; ++ai) {
;             const int rbase = u.pm * 256 + ai * 128 + wr * 64 + fr;
;             const int b = batch_of(rbase);
;             f32x4 gt[2][2], gh[2][2];
; #pragma unroll
;             for (int bj = 0; bj < 2; ++bj) {
;                 const int c0 = c00 + bj * 128;
;                 const float* gp = gate + (size_t)b * 6144 + c0;
;                 gt[bj][0] = *(const f32x4*)gp; gt[bj][1] = *(const f32x4*)(gp + 4);
;                 if (Hn) {
;                     const float* sp = scn + (size_t)b * 6144 + c0;
;                     gh[bj][0] = *(const f32x4*)(gn + c0) * (*(const f32x4*)sp + 1.f); gh[bj][1] = *(const f32x4*)(gn + c0 + 4) * (*(const f32x4*)(sp + 4) + 1.f);
;                 }
;             }
; #pragma unroll
;             for (int mp = 0; mp < 2; ++mp) {
;                 f32x4 xv[2][2][2];
; #pragma unroll
;                 for (int m2 = 0; m2 < 2; ++m2) {
;                     const int r = rbase + 16 * (2 * mp + m2);
;                     const float* xo = from_input ? ((r < MP) ? xp + (size_t)r * DM : xs + (size_t)(r - MP) * DM) : xbuf + (size_t)r * DM;
; #pragma unroll
;                     for (int bj = 0; bj < 2; ++bj) { xv[m2][bj][0] = *(const f32x4*)(xo + c00 + bj * 128); xv[m2][bj][1] = *(const f32x4*)(xo + c00 + bj * 128 + 4); }
;                 }
.LBB0_1860:
	s_lshl_b32 s28, s57, 8
	s_add_i32 s28, s28, s37
	s_add_i32 s3, s28, 0xffff0000
	s_lshr_b32 s3, s3, 6
	v_or_b32_e32 v240, s28, v4
	s_ashr_i32 s2, s28, 12
	s_add_i32 s3, s3, 16
	v_mov_b32_e32 v6, s3
	v_mov_b32_e32 v7, s2
	v_cmp_gt_i32_e32 vcc, s89, v240
	v_lshl_or_b32 v234, s56, 8, v217
	s_movk_i32 s29, 0x6000
	v_cndmask_b32_e32 v10, v6, v7, vcc
	v_mov_b64_e32 v[6:7], s[22:23]
	v_ashrrev_i32_e32 v235, 31, v234
	v_mad_i64_i32 v[6:7], s[2:3], v10, s29, v[6:7]
	v_lshl_add_u64 v[8:9], v[234:235], 2, v[6:7]
	global_load_dwordx4 v[174:177], v[8:9], off offset:16
	global_load_dwordx4 v[178:181], v[8:9], off
	v_mov_b64_e32 v[6:7], s[24:25]
	v_mad_i64_i32 v[6:7], s[2:3], v10, s29, v[6:7]
	v_readlane_b32 s2, v255, 32
	v_readlane_b32 s3, v255, 33
	s_andn2_b64 vcc, exec, s[2:3]
	v_lshlrev_b64 v[236:237], 2, v[234:235]
	v_cndmask_b32_e64 v10, 0, 1, s[2:3]
	v_readlane_b32 s2, v253, 33
	v_readlane_b32 s3, v253, 34
	v_mov_b32_e32 v22, 0
	v_cmp_ne_u32_e64 s[42:43], 1, v10
	v_lshl_add_u64 v[44:45], s[2:3], 0, v[236:237]
	v_mov_b32_e32 v23, 0
	v_mov_b32_e32 v24, 0
	v_mov_b32_e32 v25, 0
	v_mov_b32_e32 v26, 0
	v_mov_b32_e32 v27, 0
	v_mov_b32_e32 v28, 0
	v_mov_b32_e32 v29, 0
	v_ashrrev_i32_e32 v241, 31, v240
	v_lshlrev_b64 v[182:183], 12, v[240:241]
	v_or_b32_e32 v242, 16, v240
	v_lshl_add_u64 v[182:183], s[92:93], 0, v[182:183]
	v_ashrrev_i32_e32 v243, 31, v242
	v_lshl_add_u64 v[246:247], v[182:183], 0, v[236:237]
	v_lshlrev_b64 v[182:183], 12, v[242:243]
	v_lshl_add_u64 v[182:183], s[92:93], 0, v[182:183]
	v_lshl_add_u64 v[244:245], v[182:183], 0, v[236:237]
	global_load_dwordx4 v[206:209], v[246:247], off offset:16
	global_load_dwordx4 v[210:213], v[246:247], off
	global_load_dwordx4 v[198:201], v[246:247], off offset:528
	global_load_dwordx4 v[202:205], v[246:247], off offset:512
	global_load_dwordx4 v[190:193], v[244:245], off offset:16
	global_load_dwordx4 v[194:197], v[244:245], off
	global_load_dwordx4 v[182:185], v[244:245], off offset:528
	global_load_dwordx4 v[186:189], v[244:245], off offset:512
	s_cbranch_vccnz .LBB0_1862
	v_lshl_add_u64 v[14:15], v[6:7], 0, v[236:237]
	global_load_dwordx4 v[10:13], v[14:15], off
	s_nop 0
	global_load_dwordx4 v[14:17], v[14:15], off offset:16
	s_nop 0
	global_load_dwordx4 v[18:21], v[44:45], off
	global_load_dwordx4 v[26:29], v[44:45], off offset:16
	s_waitcnt vmcnt(0)
	v_pk_add_f32 v[12:13], v[12:13], 1.0 op_sel_hi:[1,0]
	v_pk_add_f32 v[10:11], v[10:11], 1.0 op_sel_hi:[1,0]
	v_pk_add_f32 v[16:17], v[16:17], 1.0 op_sel_hi:[1,0]
	v_pk_add_f32 v[14:15], v[14:15], 1.0 op_sel_hi:[1,0]
	v_pk_mul_f32 v[24:25], v[20:21], v[12:13]
	v_pk_mul_f32 v[22:23], v[18:19], v[10:11]
	v_pk_mul_f32 v[28:29], v[28:29], v[16:17]
	v_pk_mul_f32 v[26:27], v[26:27], v[14:15]

;     __device__ __forceinline__ void operator()(const f32x4 (&acc)[2][2][4][2], const Unit& u, int wr, int wc, int fr, int fq) const {
;     ...
; #pragma unroll
;                 for (int m2 = 0; m2 < 2; ++m2) {
;                     const int m = 2 * mp + m2;
;                     const int r = rbase + 16 * m;
;                     float ss = 0.f;
; #pragma unroll
;                     for (int bj = 0; bj < 2; ++bj) {
;                         const int c0 = c00 + bj * 128;
;                         float* xn = xdst + (size_t)r * DM + c0;
;                         const f32x4 y0 = xv[m2][bj][0] + gt[bj][0] * acc[ai][bj][m][0], y1 = xv[m2][bj][1] + gt[bj][1] * acc[ai][bj][m][1];
;                         *(f32x4*)xn = y0; *(f32x4*)(xn + 4) = y1;
.LBB0_1865:
	s_mov_b64 s[2:3], -1
	s_and_b64 vcc, exec, s[72:73]
	s_waitcnt vmcnt(0)
	v_pk_fma_f32 v[208:209], v[164:165], v[176:177], v[208:209]
	v_pk_fma_f32 v[212:213], v[160:161], v[180:181], v[212:213]
	v_pk_fma_f32 v[210:211], v[158:159], v[178:179], v[210:211]
	v_pk_fma_f32 v[206:207], v[162:163], v[174:175], v[206:207]
	v_pk_fma_f32 v[162:163], v[154:155], v[170:171], v[202:203]
	v_pk_fma_f32 v[158:159], v[150:151], v[166:167], v[198:199]
	global_store_dwordx4 v[246:247], v[210:213], off nt
	global_store_dwordx4 v[246:247], v[206:209], off offset:16 nt
	s_cbranch_vccz .LBB0_1867
	v_pk_fma_f32 v[164:165], v[156:157], v[172:173], v[204:205]
	v_pk_fma_f32 v[160:161], v[152:153], v[168:169], v[200:201]
	global_store_dwordx4 v[246:247], v[162:165], off offset:512 nt
	global_store_dwordx4 v[246:247], v[158:161], off offset:528 nt
	s_mov_b64 s[2:3], 0
